# v105: static raise for waves 0-3 set at the start of the GEMM phase preamble (covers the first stage loads too) instead of just before the tile loop
# speedup vs baseline: 1.0010x; 1.0010x over previous
.LBB0_381:
	s_xor_b64 s[14:15], s[22:23], -1
	v_writelane_b32 v255, s14, 45
	s_and_b64 vcc, exec, s[10:11]
	s_nop 0
	v_writelane_b32 v255, s15, 46
	s_cbranch_vccz .LBB0_799
	v_readlane_b32 vcc_lo, v254, 63
	s_cmp_lt_u32 vcc_lo, 4
	s_cbranch_scc0 .Lprio_done
	s_setprio 1
.Lprio_done:
	v_writelane_b32 v255, s72, 57
	v_lshlrev_b32_e32 v2, 5, v2
	s_waitcnt vmcnt(8)
	v_and_b32_e32 v17, 32, v2
	v_writelane_b32 v255, s73, 58
	v_lshlrev_b32_e32 v2, 6, v5
	v_writelane_b32 v255, s20, 51
	v_lshlrev_b32_e32 v7, 5, v7
	v_sub_u32_e32 v2, v3, v2
	v_writelane_b32 v255, s70, 34
	v_and_b32_e32 v14, 32, v7
	v_lshlrev_b32_e32 v7, 6, v10
	s_ashr_i32 s10, s0, 6
	v_ashrrev_i16_sdwa v2, v226, sext(v2) dst_sel:DWORD dst_unused:UNUSED_PAD src0_sel:DWORD src1_sel:BYTE_0
	v_writelane_b32 v255, s71, 35
	v_sub_u32_e32 v7, v8, v7
	s_lshl_b32 s56, s10, 10
	s_waitcnt vmcnt(3)
	v_bfe_i32 v18, v2, 0, 16
	v_writelane_b32 v255, s68, 32
	v_ashrrev_i16_sdwa v7, v226, sext(v7) dst_sel:DWORD dst_unused:UNUSED_PAD src0_sel:DWORD src1_sel:BYTE_0
	v_add_u32_e32 v2, v17, v18
	v_mul_lo_u32 v3, v6, s6
	s_add_i32 s57, s56, 0
	v_writelane_b32 v255, s69, 33
	v_bfe_i32 v15, v7, 0, 16
	v_add_lshl_u32 v176, v3, v2, 1
	s_add_i32 m0, s57, 0x10000
	v_writelane_b32 v255, s80, 29
	v_add_u32_e32 v7, v14, v15
	v_mul_lo_u32 v8, v11, s6
	s_ashr_i32 s1, s0, 8
	s_lshl_b64 s[50:51], s[62:63], 8
	s_lshl_b64 s[70:71], s[6:7], 8
	global_load_lds_dwordx4 v176, s[8:9]
	s_add_i32 m0, s57, 0x12000
	v_writelane_b32 v255, s67, 26
	v_add_lshl_u32 v172, v8, v7, 1
	s_add_u32 s14, s8, s70
	v_writelane_b32 v255, s58, 22
	global_load_lds_dwordx4 v172, s[8:9]
	s_addc_u32 s15, s9, s71
	s_add_i32 m0, s57, 0x14000
	v_writelane_b32 v255, s59, 23
	v_mul_lo_u32 v16, v9, s62
	v_mul_lo_u32 v19, v4, s62
	v_mov_b32_e32 v177, v1
	v_mov_b32_e32 v173, v1
	global_load_lds_dwordx4 v176, s[14:15]
	s_add_i32 m0, s57, 0x16000
	s_add_i32 s58, s57, 0x2000
	v_add_lshl_u32 v170, v7, v16, 1
	v_add_lshl_u32 v174, v2, v19, 1
	v_lshl_add_u64 v[6:7], s[14:15], 0, v[176:177]
	v_lshl_add_u64 v[8:9], s[14:15], 0, v[172:173]
	global_load_lds_dwordx4 v172, s[14:15]
	s_mov_b32 m0, s57
	s_add_u32 s14, s2, s50
	global_load_lds_dwordx4 v174, s[2:3]
	s_mov_b32 m0, s58
	s_addc_u32 s15, s3, s51
	s_add_i32 s59, s57, 0x4000
	global_load_lds_dwordx4 v170, s[2:3]
	s_mov_b32 m0, s59
	s_add_i32 s60, s57, 0x6000
	global_load_lds_dwordx4 v174, s[14:15]
	s_mov_b32 m0, s60
	s_cmp_eq_u32 s1, 1
	global_load_lds_dwordx4 v170, s[14:15]
	s_cselect_b64 s[14:15], -1, 0
	v_mov_b32_e32 v175, v1
	v_mov_b32_e32 v171, v1
	v_writelane_b32 v255, s14, 27
	v_lshl_add_u64 v[2:3], s[8:9], 0, v[176:177]
	v_lshl_add_u64 v[4:5], s[8:9], 0, v[172:173]
	v_lshl_add_u64 v[10:11], s[2:3], 0, v[174:175]
	v_lshl_add_u64 v[12:13], s[2:3], 0, v[170:171]
	v_writelane_b32 v255, s15, 28
	s_cmp_lg_u32 s1, 1
	s_cbranch_scc1 .LBB0_384
	s_barrier
